# GEMM phase preambles (W1, CIN, ABIN): sum-of-squares partials of all tiles of the workgroup loaded together with one wait
# baseline (speedup 1.0000x reference)
; #define PH_BEGIN(n) if (ph_lo <= (n) && (n) < ph_hi) { LAUNDER(q); char* ws = q.ws; (void)ws;
; DI void norm_prepass(const float* __restrict__ ss, const pg8::StaticOrder& S, LAS float* tab) {
;     ...
;   for (int i = 0; i < 8 && S.next(i, u); ++i) {
;     const f32x4* sp = (const f32x4*)(ss + (size_t)(u.pm * 256 + row) * 16 + half * 8);
;     const f32x4 a = sp[0], b = sp[1];
; __global__ void __launch_bounds__(512) mega(Params p, int ph_lo, int ph_hi) {
;     ...
;     } else {
;       PH_BEGIN(pb + 1)
;         run_gemm<EPI_CIN>(lds, (const u16*)(ws + B_XR), (const u16*)(ws + W_CIN) + (size_t)li * 3072 * 1024, 3072, 1024, q, nullptr, (const float*)(ws + TB_SSA), nullptr);
.LBB0_335:
	s_lshr_b32 s2, s51, 1
	v_writelane_b32 v237, s2, 4
	s_lshl_b32 s4, s51, 3
	v_readlane_b32 s10, v241, 29
	v_writelane_b32 v237, s3, 5
	s_and_b32 s2, s51, 1
	s_cmp_eq_u32 s2, 0
	s_cselect_b64 s[6:7], -1, 0
	v_writelane_b32 v237, s6, 6
	s_cmp_eq_u32 s2, 1
	s_cselect_b64 s[2:3], -1, 0
	v_writelane_b32 v237, s7, 7
	s_or_b32 s6, s4, 2
	v_readlane_b32 s11, v241, 30
	s_cmp_le_i32 s10, s6
	v_writelane_b32 v237, s4, 8
	s_cselect_b64 s[4:5], -1, 0
	s_cmp_lt_i32 s6, s11
	s_cselect_b64 s[6:7], -1, 0
	s_and_b64 vcc, exec, s[2:3]
	s_mov_b64 s[2:3], 0
	v_writelane_b32 v237, s2, 9
	s_and_b64 s[6:7], s[4:5], s[6:7]
	s_mov_b64 s[4:5], -1
	v_writelane_b32 v237, s3, 10
	v_writelane_b32 v237, s51, 11
	s_cbranch_vccz .LBB0_652
	s_andn2_b64 vcc, exec, s[6:7]
	s_cbranch_vccnz .LBB0_556
	s_mov_b64 s[2:3], 0
	v_readlane_b32 s4, v241, 1
	v_readlane_b32 s5, v241, 2
	s_add_u32 s10, s4, s2
	s_addc_u32 s11, s5, s3
	v_readlane_b32 s4, v241, 47
	v_readlane_b32 s5, v241, 48
	v_mov_b32_e32 v3, v182
	v_cmp_ne_u32_e64 s[2:3], 1, v183
	s_andn2_b64 vcc, exec, s[4:5]
	s_cbranch_vccnz .LBB0_362
	v_and_b32_e32 v14, 1, v3
	v_lshlrev_b32_e32 v144, 5, v14
	s_waitcnt lgkmcnt(0)
	v_lshl_add_u64 v[0:1], s[10:11], 0, v[144:145]
	s_mov_b64 s[4:5], 0x5fa4100
	v_ashrrev_i32_e32 v2, 1, v3
	v_lshl_add_u64 v[0:1], v[0:1], 0, s[4:5]
	v_readlane_b32 s4, v241, 49
	v_lshlrev_b32_e32 v3, 2, v3
	s_nop 0
	v_add_u32_e32 v4, s4, v2
	v_ashrrev_i32_e32 v5, 31, v4
	v_lshlrev_b64 v[4:5], 6, v[4:5]
	v_lshl_add_u64 v[4:5], v[0:1], 0, v[4:5]
	global_load_dwordx4 v[6:9], v[4:5], off
	global_load_dwordx4 v[10:13], v[4:5], off offset:16
	v_readlane_b32 s12, v239, 42
	v_readlane_b32 s13, v239, 43
	s_nop 3
	s_andn2_b64 vcc, exec, s[12:13]
	s_cbranch_vccnz .Lpf_cin_done
	v_readlane_b32 s9, v240, 57
	s_nop 3
	v_add_u32_e32 v72, s9, v2
	v_ashrrev_i32_e32 v73, 31, v72
	v_lshlrev_b64 v[72:73], 6, v[72:73]
	v_lshl_add_u64 v[72:73], v[0:1], 0, v[72:73]
	global_load_dwordx4 v[16:19], v[72:73], off
	global_load_dwordx4 v[20:23], v[72:73], off offset:16
	v_readlane_b32 s12, v239, 46
	v_readlane_b32 s13, v239, 47
	s_nop 3
	s_andn2_b64 vcc, exec, s[12:13]
	s_cbranch_vccnz .Lpf_cin_done
	v_readlane_b32 s9, v240, 58
	s_nop 3
	v_add_u32_e32 v72, s9, v2
	v_ashrrev_i32_e32 v73, 31, v72
	v_lshlrev_b64 v[72:73], 6, v[72:73]
	v_lshl_add_u64 v[72:73], v[0:1], 0, v[72:73]
	global_load_dwordx4 v[24:27], v[72:73], off
	global_load_dwordx4 v[28:31], v[72:73], off offset:16
	v_readlane_b32 s12, v239, 57
	v_readlane_b32 s13, v239, 58
	s_nop 3
	s_andn2_b64 vcc, exec, s[12:13]
	s_cbranch_vccnz .Lpf_cin_done
	v_readlane_b32 s9, v240, 59
	s_nop 3
	v_add_u32_e32 v72, s9, v2
	v_ashrrev_i32_e32 v73, 31, v72
	v_lshlrev_b64 v[72:73], 6, v[72:73]
	v_lshl_add_u64 v[72:73], v[0:1], 0, v[72:73]
	global_load_dwordx4 v[32:35], v[72:73], off
	global_load_dwordx4 v[36:39], v[72:73], off offset:16
	v_readlane_b32 s12, v238, 3
	v_readlane_b32 s13, v238, 4
	s_nop 3
	s_andn2_b64 vcc, exec, s[12:13]
	s_cbranch_vccnz .Lpf_cin_done
	v_readlane_b32 s9, v240, 60
	s_nop 3
	v_add_u32_e32 v72, s9, v2
	v_ashrrev_i32_e32 v73, 31, v72
	v_lshlrev_b64 v[72:73], 6, v[72:73]
	v_lshl_add_u64 v[72:73], v[0:1], 0, v[72:73]
	global_load_dwordx4 v[40:43], v[72:73], off
	global_load_dwordx4 v[44:47], v[72:73], off offset:16
	v_readlane_b32 s12, v238, 9
	v_readlane_b32 s13, v238, 10
	s_nop 3
	s_andn2_b64 vcc, exec, s[12:13]
	s_cbranch_vccnz .Lpf_cin_done
	v_readlane_b32 s9, v240, 61
	s_nop 3
	v_add_u32_e32 v72, s9, v2
	v_ashrrev_i32_e32 v73, 31, v72
	v_lshlrev_b64 v[72:73], 6, v[72:73]
	v_lshl_add_u64 v[72:73], v[0:1], 0, v[72:73]
	global_load_dwordx4 v[48:51], v[72:73], off
	global_load_dwordx4 v[52:55], v[72:73], off offset:16
	v_readlane_b32 s12, v238, 15
	v_readlane_b32 s13, v238, 16
	s_nop 3
	s_andn2_b64 vcc, exec, s[12:13]
	s_cbranch_vccnz .Lpf_cin_done
	v_readlane_b32 s9, v240, 62
	s_nop 3
	v_add_u32_e32 v72, s9, v2
	v_ashrrev_i32_e32 v73, 31, v72
	v_lshlrev_b64 v[72:73], 6, v[72:73]
	v_lshl_add_u64 v[72:73], v[0:1], 0, v[72:73]
	global_load_dwordx4 v[56:59], v[72:73], off
	global_load_dwordx4 v[60:63], v[72:73], off offset:16
	v_readlane_b32 s12, v238, 21
	v_readlane_b32 s13, v238, 22
	s_nop 3
	s_andn2_b64 vcc, exec, s[12:13]
	s_cbranch_vccnz .Lpf_cin_done
	v_readlane_b32 s9, v240, 63
	s_nop 3
	v_add_u32_e32 v72, s9, v2
	v_ashrrev_i32_e32 v73, 31, v72
	v_lshlrev_b64 v[72:73], 6, v[72:73]
	v_lshl_add_u64 v[72:73], v[0:1], 0, v[72:73]
	global_load_dwordx4 v[64:67], v[72:73], off
	global_load_dwordx4 v[68:71], v[72:73], off offset:16

; DI void norm_prepass(const float* __restrict__ ss, const pg8::StaticOrder& S, LAS float* tab) {
;     ...
;   for (int i = 0; i < 8 && S.next(i, u); ++i) {
;     const f32x4* sp = (const f32x4*)(ss + (size_t)(u.pm * 256 + row) * 16 + half * 8);
;     const f32x4 a = sp[0], b = sp[1];
;     float t = a[0]; t += a[1]; t += a[2]; t += a[3]; t += b[0]; t += b[1]; t += b[2]; t += b[3];
;     const float o = shx(t, 1, tid & 63);
;     const float tot = half ? (o + t) : (t + o);
;     if (!half) tab[i * 256 + row] = rsqrtf(tot * (1.f / 1024.f) + EPS);
.LBB0_340:
	s_or_b64 exec, exec, s[12:13]
	v_readlane_b32 s12, v239, 42
	v_readlane_b32 s13, v239, 43
	s_andn2_b64 vcc, exec, s[12:13]
	s_cbranch_vccnz .LBB0_362
	v_readlane_b32 s9, v240, 57
	s_waitcnt lgkmcnt(0)
	s_nop 0
	v_add_f32_e32 v5, v16, v17
	v_add_f32_e32 v5, v18, v5
	v_add_f32_e32 v5, v19, v5
	v_add_f32_e32 v5, v20, v5
	v_add_f32_e32 v5, v21, v5
	v_add_f32_e32 v5, v22, v5
	v_add_f32_e32 v5, v23, v5
	ds_bpermute_b32 v6, v4, v5
	s_and_saveexec_b64 s[12:13], s[4:5]
	s_cbranch_execz .LBB0_343
	s_waitcnt lgkmcnt(0)
	v_add_f32_e32 v5, v5, v6
	v_fmamk_f32 v5, v5, 0x3a800000, v184
	s_mov_b32 s9, 0x800000
	v_mul_f32_e32 v6, 0x4b800000, v5
	v_cmp_gt_f32_e32 vcc, s9, v5
	s_nop 1
	v_cndmask_b32_e32 v5, v5, v6, vcc
	v_rsq_f32_e32 v5, v5
	s_nop 0
	v_mul_f32_e32 v6, 0x45800000, v5
	v_cndmask_b32_e32 v5, v5, v6, vcc
	ds_write_b32 v3, v5 offset:1024
.LBB0_343:
	s_or_b64 exec, exec, s[12:13]
	v_readlane_b32 s12, v239, 46
	v_readlane_b32 s13, v239, 47
	s_andn2_b64 vcc, exec, s[12:13]
	s_cbranch_vccnz .LBB0_362
	v_readlane_b32 s9, v240, 58
	s_waitcnt lgkmcnt(0)
	s_nop 0
	v_add_f32_e32 v5, v24, v25
	v_add_f32_e32 v5, v26, v5
	v_add_f32_e32 v5, v27, v5
	v_add_f32_e32 v5, v28, v5
	v_add_f32_e32 v5, v29, v5
	v_add_f32_e32 v5, v30, v5
	v_add_f32_e32 v5, v31, v5
	ds_bpermute_b32 v6, v4, v5
	s_and_saveexec_b64 s[12:13], s[4:5]
	s_cbranch_execz .LBB0_346
	s_waitcnt lgkmcnt(0)
	v_add_f32_e32 v5, v5, v6
	v_fmamk_f32 v5, v5, 0x3a800000, v184
	s_mov_b32 s9, 0x800000
	v_mul_f32_e32 v6, 0x4b800000, v5
	v_cmp_gt_f32_e32 vcc, s9, v5
	s_nop 1
	v_cndmask_b32_e32 v5, v5, v6, vcc
	v_rsq_f32_e32 v5, v5
	s_nop 0
	v_mul_f32_e32 v6, 0x45800000, v5
	v_cndmask_b32_e32 v5, v5, v6, vcc
	ds_write_b32 v3, v5 offset:2048
.LBB0_346:
	s_or_b64 exec, exec, s[12:13]
	v_readlane_b32 s12, v239, 57
	v_readlane_b32 s13, v239, 58
	s_andn2_b64 vcc, exec, s[12:13]
	s_cbranch_vccnz .LBB0_362
	v_readlane_b32 s9, v240, 59
	s_waitcnt lgkmcnt(0)
	s_nop 0
	v_add_f32_e32 v5, v32, v33
	v_add_f32_e32 v5, v34, v5
	v_add_f32_e32 v5, v35, v5
	v_add_f32_e32 v5, v36, v5
	v_add_f32_e32 v5, v37, v5
	v_add_f32_e32 v5, v38, v5
	v_add_f32_e32 v5, v39, v5
	ds_bpermute_b32 v6, v4, v5
	s_and_saveexec_b64 s[12:13], s[4:5]
	s_cbranch_execz .LBB0_349
	s_waitcnt lgkmcnt(0)
	v_add_f32_e32 v5, v5, v6
	v_fmamk_f32 v5, v5, 0x3a800000, v184
	s_mov_b32 s9, 0x800000
	v_mul_f32_e32 v6, 0x4b800000, v5
	v_cmp_gt_f32_e32 vcc, s9, v5
	s_nop 1
	v_cndmask_b32_e32 v5, v5, v6, vcc
	v_rsq_f32_e32 v5, v5
	s_nop 0
	v_mul_f32_e32 v6, 0x45800000, v5
	v_cndmask_b32_e32 v5, v5, v6, vcc
	ds_write_b32 v3, v5 offset:3072
.LBB0_349:
	s_or_b64 exec, exec, s[12:13]
	v_readlane_b32 s12, v238, 3
	v_readlane_b32 s13, v238, 4
	s_andn2_b64 vcc, exec, s[12:13]
	s_cbranch_vccnz .LBB0_362
	v_readlane_b32 s9, v240, 60
	s_waitcnt lgkmcnt(0)
	s_nop 0
	v_add_f32_e32 v5, v40, v41
	v_add_f32_e32 v5, v42, v5
	v_add_f32_e32 v5, v43, v5
	v_add_f32_e32 v5, v44, v5
	v_add_f32_e32 v5, v45, v5
	v_add_f32_e32 v5, v46, v5
	v_add_f32_e32 v5, v47, v5
	ds_bpermute_b32 v6, v4, v5
	s_and_saveexec_b64 s[12:13], s[4:5]
	s_cbranch_execz .LBB0_352
	s_waitcnt lgkmcnt(0)
	v_add_f32_e32 v5, v5, v6
	v_fmamk_f32 v5, v5, 0x3a800000, v184
	s_mov_b32 s9, 0x800000
	v_mul_f32_e32 v6, 0x4b800000, v5
	v_cmp_gt_f32_e32 vcc, s9, v5
	s_nop 1
	v_cndmask_b32_e32 v5, v5, v6, vcc
	v_rsq_f32_e32 v5, v5
	s_nop 0
	v_mul_f32_e32 v6, 0x45800000, v5
	v_cndmask_b32_e32 v5, v5, v6, vcc
	ds_write_b32 v3, v5 offset:4096
.LBB0_352:
	s_or_b64 exec, exec, s[12:13]
	v_readlane_b32 s12, v238, 9
	v_readlane_b32 s13, v238, 10
	s_andn2_b64 vcc, exec, s[12:13]
	s_cbranch_vccnz .LBB0_362
	v_readlane_b32 s9, v240, 61
	s_waitcnt lgkmcnt(0)
	s_nop 0
	v_add_f32_e32 v5, v48, v49
	v_add_f32_e32 v5, v50, v5
	v_add_f32_e32 v5, v51, v5
	v_add_f32_e32 v5, v52, v5
	v_add_f32_e32 v5, v53, v5
	v_add_f32_e32 v5, v54, v5
	v_add_f32_e32 v5, v55, v5
	ds_bpermute_b32 v6, v4, v5
	s_and_saveexec_b64 s[12:13], s[4:5]
	s_cbranch_execz .LBB0_355
	s_waitcnt lgkmcnt(0)
	v_add_f32_e32 v5, v5, v6
	v_fmamk_f32 v5, v5, 0x3a800000, v184
	s_mov_b32 s9, 0x800000
	v_mul_f32_e32 v6, 0x4b800000, v5
	v_cmp_gt_f32_e32 vcc, s9, v5
	s_nop 1
	v_cndmask_b32_e32 v5, v5, v6, vcc
	v_rsq_f32_e32 v5, v5
	s_nop 0
	v_mul_f32_e32 v6, 0x45800000, v5
	v_cndmask_b32_e32 v5, v5, v6, vcc
	ds_write_b32 v3, v5 offset:5120
.LBB0_355:
	s_or_b64 exec, exec, s[12:13]
	v_readlane_b32 s12, v238, 15
	v_readlane_b32 s13, v238, 16
	s_andn2_b64 vcc, exec, s[12:13]
	s_cbranch_vccnz .LBB0_362
	v_readlane_b32 s9, v240, 62
	s_waitcnt lgkmcnt(0)
	s_nop 0
	v_add_f32_e32 v5, v56, v57
	v_add_f32_e32 v5, v58, v5
	v_add_f32_e32 v5, v59, v5
	v_add_f32_e32 v5, v60, v5
	v_add_f32_e32 v5, v61, v5
	v_add_f32_e32 v5, v62, v5
	v_add_f32_e32 v5, v63, v5
	ds_bpermute_b32 v6, v4, v5
	s_and_saveexec_b64 s[12:13], s[4:5]
	s_cbranch_execz .LBB0_358
	s_waitcnt lgkmcnt(0)
	v_add_f32_e32 v5, v5, v6
	v_fmamk_f32 v5, v5, 0x3a800000, v184
	s_mov_b32 s9, 0x800000
	v_mul_f32_e32 v6, 0x4b800000, v5
	v_cmp_gt_f32_e32 vcc, s9, v5
	s_nop 1
	v_cndmask_b32_e32 v5, v5, v6, vcc
	v_rsq_f32_e32 v5, v5
	s_nop 0
	v_mul_f32_e32 v6, 0x45800000, v5
	v_cndmask_b32_e32 v5, v5, v6, vcc
	ds_write_b32 v3, v5 offset:6144
.LBB0_358:
	s_or_b64 exec, exec, s[12:13]
	v_readlane_b32 s12, v238, 21
	v_readlane_b32 s13, v238, 22
	s_andn2_b64 vcc, exec, s[12:13]
	s_cbranch_vccnz .LBB0_362
	v_readlane_b32 s9, v240, 63
	s_waitcnt lgkmcnt(0)
	s_nop 0
	v_add_f32_e32 v0, v64, v65
	v_add_f32_e32 v0, v66, v0
	v_add_f32_e32 v0, v67, v0
	v_add_f32_e32 v0, v68, v0
	v_add_f32_e32 v0, v69, v0
	v_add_f32_e32 v0, v70, v0
	v_add_f32_e32 v0, v71, v0
	ds_bpermute_b32 v1, v4, v0
	s_and_saveexec_b64 s[12:13], s[4:5]
	s_cbranch_execz .LBB0_361
	s_waitcnt lgkmcnt(0)
	v_add_f32_e32 v0, v0, v1
	v_fmamk_f32 v0, v0, 0x3a800000, v184
	s_mov_b32 s4, 0x800000
	v_mul_f32_e32 v1, 0x4b800000, v0
	v_cmp_gt_f32_e32 vcc, s4, v0
	s_nop 1
	v_cndmask_b32_e32 v0, v0, v1, vcc
	v_rsq_f32_e32 v0, v0
	s_nop 0
	v_mul_f32_e32 v1, 0x45800000, v0
	v_cndmask_b32_e32 v0, v0, v1, vcc
	ds_write_b32 v3, v0 offset:7168

; #define PH_BEGIN(n) if (ph_lo <= (n) && (n) < ph_hi) { LAUNDER(q); char* ws = q.ws; (void)ws;
; DI void norm_prepass(const float* __restrict__ ss, const pg8::StaticOrder& S, LAS float* tab) {
;     ...
;   for (int i = 0; i < 8 && S.next(i, u); ++i) {
;     const f32x4* sp = (const f32x4*)(ss + (size_t)(u.pm * 256 + row) * 16 + half * 8);
;     const f32x4 a = sp[0], b = sp[1];
; __global__ void __launch_bounds__(512) mega(Params p, int ph_lo, int ph_hi) {
;     ...
;     if (even) {
;       PH_BEGIN(pb + 1)
;         run_gemm<EPI_ABIN>(lds, (const u16*)(ws + B_XR), (const u16*)(ws + W_ABIN) + (size_t)li * 2304 * 1024, 2304, 1024, q, nullptr, (const float*)(ws + TB_SSA), nullptr);
.LBB0_655:
	s_andn2_b64 vcc, exec, s[2:3]
	s_cbranch_vccnz .LBB0_1163
	s_mov_b64 s[2:3], 0
	v_readlane_b32 s4, v241, 1
	v_readlane_b32 s5, v241, 2
	s_add_u32 s10, s4, s2
	s_addc_u32 s11, s5, s3
	v_readlane_b32 s4, v240, 27
	v_readlane_b32 s5, v240, 28
	v_mov_b32_e32 v3, v182
	s_andn2_b64 vcc, exec, s[4:5]
	v_cndmask_b32_e64 v0, 0, 1, s[4:5]
	v_cmp_ne_u32_e64 s[2:3], 1, v0
	s_cbranch_vccnz .LBB0_681
	v_and_b32_e32 v14, 1, v3
	v_lshlrev_b32_e32 v144, 5, v14
	s_waitcnt lgkmcnt(0)
	v_lshl_add_u64 v[0:1], s[10:11], 0, v[144:145]
	s_mov_b64 s[4:5], 0x5fa4100
	v_ashrrev_i32_e32 v2, 1, v3
	v_lshl_add_u64 v[0:1], v[0:1], 0, s[4:5]
	v_readlane_b32 s4, v240, 29
	v_lshlrev_b32_e32 v3, 2, v3
	s_nop 0
	v_add_u32_e32 v4, s4, v2
	v_ashrrev_i32_e32 v5, 31, v4
	v_lshlrev_b64 v[4:5], 6, v[4:5]
	v_lshl_add_u64 v[4:5], v[0:1], 0, v[4:5]
	global_load_dwordx4 v[6:9], v[4:5], off
	global_load_dwordx4 v[10:13], v[4:5], off offset:16
	v_readlane_b32 s6, v238, 53
	v_readlane_b32 s7, v238, 54
	s_nop 3
	s_andn2_b64 vcc, exec, s[6:7]
	s_cbranch_vccnz .Lpf_abin_done
	v_readlane_b32 s6, v239, 0
	s_nop 3
	v_add_u32_e32 v72, s6, v2
	v_ashrrev_i32_e32 v73, 31, v72
	v_lshlrev_b64 v[72:73], 6, v[72:73]
	v_lshl_add_u64 v[72:73], v[0:1], 0, v[72:73]
	global_load_dwordx4 v[16:19], v[72:73], off
	global_load_dwordx4 v[20:23], v[72:73], off offset:16
	v_readlane_b32 s6, v239, 49
	v_readlane_b32 s7, v239, 50
	s_nop 3
	s_andn2_b64 vcc, exec, s[6:7]
	s_cbranch_vccnz .Lpf_abin_done
	v_readlane_b32 s6, v239, 1
	s_nop 3
	v_add_u32_e32 v72, s6, v2
	v_ashrrev_i32_e32 v73, 31, v72
	v_lshlrev_b64 v[72:73], 6, v[72:73]
	v_lshl_add_u64 v[72:73], v[0:1], 0, v[72:73]
	global_load_dwordx4 v[24:27], v[72:73], off
	global_load_dwordx4 v[28:31], v[72:73], off offset:16
	v_readlane_b32 s6, v239, 59
	v_readlane_b32 s7, v239, 60
	s_nop 3
	s_andn2_b64 vcc, exec, s[6:7]
	s_cbranch_vccnz .Lpf_abin_done
	v_readlane_b32 s6, v239, 2
	s_nop 3
	v_add_u32_e32 v72, s6, v2
	v_ashrrev_i32_e32 v73, 31, v72
	v_lshlrev_b64 v[72:73], 6, v[72:73]
	v_lshl_add_u64 v[72:73], v[0:1], 0, v[72:73]
	global_load_dwordx4 v[32:35], v[72:73], off
	global_load_dwordx4 v[36:39], v[72:73], off offset:16
	v_readlane_b32 s6, v238, 5
	v_readlane_b32 s7, v238, 6
	s_nop 3
	s_andn2_b64 vcc, exec, s[6:7]
	s_cbranch_vccnz .Lpf_abin_done
	v_readlane_b32 s6, v239, 3
	s_nop 3
	v_add_u32_e32 v72, s6, v2
	v_ashrrev_i32_e32 v73, 31, v72
	v_lshlrev_b64 v[72:73], 6, v[72:73]
	v_lshl_add_u64 v[72:73], v[0:1], 0, v[72:73]
	global_load_dwordx4 v[40:43], v[72:73], off
	global_load_dwordx4 v[44:47], v[72:73], off offset:16
	v_readlane_b32 s6, v238, 11
	v_readlane_b32 s7, v238, 12
	s_nop 3
	s_andn2_b64 vcc, exec, s[6:7]
	s_cbranch_vccnz .Lpf_abin_done
	v_readlane_b32 s6, v239, 4
	s_nop 3
	v_add_u32_e32 v72, s6, v2
	v_ashrrev_i32_e32 v73, 31, v72
	v_lshlrev_b64 v[72:73], 6, v[72:73]
	v_lshl_add_u64 v[72:73], v[0:1], 0, v[72:73]
	global_load_dwordx4 v[48:51], v[72:73], off
	global_load_dwordx4 v[52:55], v[72:73], off offset:16
	v_readlane_b32 s6, v238, 17
	v_readlane_b32 s7, v238, 18
	s_nop 3
	s_andn2_b64 vcc, exec, s[6:7]
	s_cbranch_vccnz .Lpf_abin_done
	v_readlane_b32 s6, v239, 5
	s_nop 3
	v_add_u32_e32 v72, s6, v2
	v_ashrrev_i32_e32 v73, 31, v72
	v_lshlrev_b64 v[72:73], 6, v[72:73]
	v_lshl_add_u64 v[72:73], v[0:1], 0, v[72:73]
	global_load_dwordx4 v[56:59], v[72:73], off
	global_load_dwordx4 v[60:63], v[72:73], off offset:16
	v_readlane_b32 s6, v238, 23
	v_readlane_b32 s7, v238, 24
	s_nop 3
	s_andn2_b64 vcc, exec, s[6:7]
	s_cbranch_vccnz .Lpf_abin_done
	v_readlane_b32 s6, v239, 6
	s_nop 3
	v_add_u32_e32 v72, s6, v2
	v_ashrrev_i32_e32 v73, 31, v72
	v_lshlrev_b64 v[72:73], 6, v[72:73]
	v_lshl_add_u64 v[72:73], v[0:1], 0, v[72:73]
	global_load_dwordx4 v[64:67], v[72:73], off
	global_load_dwordx4 v[68:71], v[72:73], off offset:16

; DI void norm_prepass(const float* __restrict__ ss, const pg8::StaticOrder& S, LAS float* tab) {
;     ...
;   for (int i = 0; i < 8 && S.next(i, u); ++i) {
;     const f32x4* sp = (const f32x4*)(ss + (size_t)(u.pm * 256 + row) * 16 + half * 8);
;     const f32x4 a = sp[0], b = sp[1];
;     float t = a[0]; t += a[1]; t += a[2]; t += a[3]; t += b[0]; t += b[1]; t += b[2]; t += b[3];
;     const float o = shx(t, 1, tid & 63);
;     const float tot = half ? (o + t) : (t + o);
;     if (!half) tab[i * 256 + row] = rsqrtf(tot * (1.f / 1024.f) + EPS);
.LBB0_659:
	s_or_b64 exec, exec, s[6:7]
	v_readlane_b32 s6, v238, 53
	v_readlane_b32 s7, v238, 54
	s_andn2_b64 vcc, exec, s[6:7]
	s_cbranch_vccnz .LBB0_681
	v_readlane_b32 s6, v239, 0
	s_waitcnt lgkmcnt(0)
	s_nop 0
	v_add_f32_e32 v5, v16, v17
	v_add_f32_e32 v5, v18, v5
	v_add_f32_e32 v5, v19, v5
	v_add_f32_e32 v5, v20, v5
	v_add_f32_e32 v5, v21, v5
	v_add_f32_e32 v5, v22, v5
	v_add_f32_e32 v5, v23, v5
	ds_bpermute_b32 v6, v4, v5
	s_and_saveexec_b64 s[6:7], s[4:5]
	s_cbranch_execz .LBB0_662
	s_waitcnt lgkmcnt(0)
	v_add_f32_e32 v5, v5, v6
	v_fmamk_f32 v5, v5, 0x3a800000, v184
	s_mov_b32 s9, 0x800000
	v_mul_f32_e32 v6, 0x4b800000, v5
	v_cmp_gt_f32_e32 vcc, s9, v5
	s_nop 1
	v_cndmask_b32_e32 v5, v5, v6, vcc
	v_rsq_f32_e32 v5, v5
	s_nop 0
	v_mul_f32_e32 v6, 0x45800000, v5
	v_cndmask_b32_e32 v5, v5, v6, vcc
	ds_write_b32 v3, v5 offset:1024
.LBB0_662:
	s_or_b64 exec, exec, s[6:7]
	v_readlane_b32 s6, v239, 49
	v_readlane_b32 s7, v239, 50
	s_andn2_b64 vcc, exec, s[6:7]
	s_cbranch_vccnz .LBB0_681
	v_readlane_b32 s6, v239, 1
	s_waitcnt lgkmcnt(0)
	s_nop 0
	v_add_f32_e32 v5, v24, v25
	v_add_f32_e32 v5, v26, v5
	v_add_f32_e32 v5, v27, v5
	v_add_f32_e32 v5, v28, v5
	v_add_f32_e32 v5, v29, v5
	v_add_f32_e32 v5, v30, v5
	v_add_f32_e32 v5, v31, v5
	ds_bpermute_b32 v6, v4, v5
	s_and_saveexec_b64 s[6:7], s[4:5]
	s_cbranch_execz .LBB0_665
	s_waitcnt lgkmcnt(0)
	v_add_f32_e32 v5, v5, v6
	v_fmamk_f32 v5, v5, 0x3a800000, v184
	s_mov_b32 s9, 0x800000
	v_mul_f32_e32 v6, 0x4b800000, v5
	v_cmp_gt_f32_e32 vcc, s9, v5
	s_nop 1
	v_cndmask_b32_e32 v5, v5, v6, vcc
	v_rsq_f32_e32 v5, v5
	s_nop 0
	v_mul_f32_e32 v6, 0x45800000, v5
	v_cndmask_b32_e32 v5, v5, v6, vcc
	ds_write_b32 v3, v5 offset:2048
.LBB0_665:
	s_or_b64 exec, exec, s[6:7]
	v_readlane_b32 s6, v239, 59
	v_readlane_b32 s7, v239, 60
	s_andn2_b64 vcc, exec, s[6:7]
	s_cbranch_vccnz .LBB0_681
	v_readlane_b32 s6, v239, 2
	s_waitcnt lgkmcnt(0)
	s_nop 0
	v_add_f32_e32 v5, v32, v33
	v_add_f32_e32 v5, v34, v5
	v_add_f32_e32 v5, v35, v5
	v_add_f32_e32 v5, v36, v5
	v_add_f32_e32 v5, v37, v5
	v_add_f32_e32 v5, v38, v5
	v_add_f32_e32 v5, v39, v5
	ds_bpermute_b32 v6, v4, v5
	s_and_saveexec_b64 s[6:7], s[4:5]
	s_cbranch_execz .LBB0_668
	s_waitcnt lgkmcnt(0)
	v_add_f32_e32 v5, v5, v6
	v_fmamk_f32 v5, v5, 0x3a800000, v184
	s_mov_b32 s9, 0x800000
	v_mul_f32_e32 v6, 0x4b800000, v5
	v_cmp_gt_f32_e32 vcc, s9, v5
	s_nop 1
	v_cndmask_b32_e32 v5, v5, v6, vcc
	v_rsq_f32_e32 v5, v5
	s_nop 0
	v_mul_f32_e32 v6, 0x45800000, v5
	v_cndmask_b32_e32 v5, v5, v6, vcc
	ds_write_b32 v3, v5 offset:3072
.LBB0_668:
	s_or_b64 exec, exec, s[6:7]
	v_readlane_b32 s6, v238, 5
	v_readlane_b32 s7, v238, 6
	s_andn2_b64 vcc, exec, s[6:7]
	s_cbranch_vccnz .LBB0_681
	v_readlane_b32 s6, v239, 3
	s_waitcnt lgkmcnt(0)
	s_nop 0
	v_add_f32_e32 v5, v40, v41
	v_add_f32_e32 v5, v42, v5
	v_add_f32_e32 v5, v43, v5
	v_add_f32_e32 v5, v44, v5
	v_add_f32_e32 v5, v45, v5
	v_add_f32_e32 v5, v46, v5
	v_add_f32_e32 v5, v47, v5
	ds_bpermute_b32 v6, v4, v5
	s_and_saveexec_b64 s[6:7], s[4:5]
	s_cbranch_execz .LBB0_671
	s_waitcnt lgkmcnt(0)
	v_add_f32_e32 v5, v5, v6
	v_fmamk_f32 v5, v5, 0x3a800000, v184
	s_mov_b32 s9, 0x800000
	v_mul_f32_e32 v6, 0x4b800000, v5
	v_cmp_gt_f32_e32 vcc, s9, v5
	s_nop 1
	v_cndmask_b32_e32 v5, v5, v6, vcc
	v_rsq_f32_e32 v5, v5
	s_nop 0
	v_mul_f32_e32 v6, 0x45800000, v5
	v_cndmask_b32_e32 v5, v5, v6, vcc
	ds_write_b32 v3, v5 offset:4096
.LBB0_671:
	s_or_b64 exec, exec, s[6:7]
	v_readlane_b32 s6, v238, 11
	v_readlane_b32 s7, v238, 12
	s_andn2_b64 vcc, exec, s[6:7]
	s_cbranch_vccnz .LBB0_681
	v_readlane_b32 s6, v239, 4
	s_waitcnt lgkmcnt(0)
	s_nop 0
	v_add_f32_e32 v5, v48, v49
	v_add_f32_e32 v5, v50, v5
	v_add_f32_e32 v5, v51, v5
	v_add_f32_e32 v5, v52, v5
	v_add_f32_e32 v5, v53, v5
	v_add_f32_e32 v5, v54, v5
	v_add_f32_e32 v5, v55, v5
	ds_bpermute_b32 v6, v4, v5
	s_and_saveexec_b64 s[6:7], s[4:5]
	s_cbranch_execz .LBB0_674
	s_waitcnt lgkmcnt(0)
	v_add_f32_e32 v5, v5, v6
	v_fmamk_f32 v5, v5, 0x3a800000, v184
	s_mov_b32 s9, 0x800000
	v_mul_f32_e32 v6, 0x4b800000, v5
	v_cmp_gt_f32_e32 vcc, s9, v5
	s_nop 1
	v_cndmask_b32_e32 v5, v5, v6, vcc
	v_rsq_f32_e32 v5, v5
	s_nop 0
	v_mul_f32_e32 v6, 0x45800000, v5
	v_cndmask_b32_e32 v5, v5, v6, vcc
	ds_write_b32 v3, v5 offset:5120
.LBB0_674:
	s_or_b64 exec, exec, s[6:7]
	v_readlane_b32 s6, v238, 17
	v_readlane_b32 s7, v238, 18
	s_andn2_b64 vcc, exec, s[6:7]
	s_cbranch_vccnz .LBB0_681
	v_readlane_b32 s6, v239, 5
	s_waitcnt lgkmcnt(0)
	s_nop 0
	v_add_f32_e32 v5, v56, v57
	v_add_f32_e32 v5, v58, v5
	v_add_f32_e32 v5, v59, v5
	v_add_f32_e32 v5, v60, v5
	v_add_f32_e32 v5, v61, v5
	v_add_f32_e32 v5, v62, v5
	v_add_f32_e32 v5, v63, v5
	ds_bpermute_b32 v6, v4, v5
	s_and_saveexec_b64 s[6:7], s[4:5]
	s_cbranch_execz .LBB0_677
	s_waitcnt lgkmcnt(0)
	v_add_f32_e32 v5, v5, v6
	v_fmamk_f32 v5, v5, 0x3a800000, v184
	s_mov_b32 s9, 0x800000
	v_mul_f32_e32 v6, 0x4b800000, v5
	v_cmp_gt_f32_e32 vcc, s9, v5
	s_nop 1
	v_cndmask_b32_e32 v5, v5, v6, vcc
	v_rsq_f32_e32 v5, v5
	s_nop 0
	v_mul_f32_e32 v6, 0x45800000, v5
	v_cndmask_b32_e32 v5, v5, v6, vcc
	ds_write_b32 v3, v5 offset:6144
.LBB0_677:
	s_or_b64 exec, exec, s[6:7]
	v_readlane_b32 s6, v238, 23
	v_readlane_b32 s7, v238, 24
	s_andn2_b64 vcc, exec, s[6:7]
	s_cbranch_vccnz .LBB0_681
	v_readlane_b32 s6, v239, 6
	s_waitcnt lgkmcnt(0)
	s_nop 0
	v_add_f32_e32 v0, v64, v65
	v_add_f32_e32 v0, v66, v0
	v_add_f32_e32 v0, v67, v0
	v_add_f32_e32 v0, v68, v0
	v_add_f32_e32 v0, v69, v0
	v_add_f32_e32 v0, v70, v0
	v_add_f32_e32 v0, v71, v0
	ds_bpermute_b32 v1, v4, v0
	s_and_saveexec_b64 s[6:7], s[4:5]
	s_cbranch_execz .LBB0_680
	s_waitcnt lgkmcnt(0)
	v_add_f32_e32 v0, v0, v1
	v_fmamk_f32 v0, v0, 0x3a800000, v184
	s_mov_b32 s4, 0x800000
	v_mul_f32_e32 v1, 0x4b800000, v0
	v_cmp_gt_f32_e32 vcc, s4, v0
	s_nop 1
	v_cndmask_b32_e32 v0, v0, v1, vcc
	v_rsq_f32_e32 v0, v0
	s_nop 0
	v_mul_f32_e32 v1, 0x45800000, v0
	v_cndmask_b32_e32 v0, v0, v1, vcc
	ds_write_b32 v3, v0 offset:7168

; #define PH_BEGIN(n) if (ph_lo <= (n) && (n) < ph_hi) { LAUNDER(q); char* ws = q.ws; (void)ws;
; DI void norm_prepass(const float* __restrict__ ss, const pg8::StaticOrder& S, LAS float* tab) {
;     ...
;   for (int i = 0; i < 8 && S.next(i, u); ++i) {
;     const f32x4* sp = (const f32x4*)(ss + (size_t)(u.pm * 256 + row) * 16 + half * 8);
;     const f32x4 a = sp[0], b = sp[1];
; __global__ void __launch_bounds__(512) mega(Params p, int ph_lo, int ph_hi) {
;     ...
;     PH_BEGIN(pb + 6)
;       run_gemm<EPI_RELU2>(lds, (const u16*)(ws + B_XR), (const u16*)(ws + W_W1) + (size_t)L * 4096 * 1024, 4096, 1024, q, nullptr, (const float*)(ws + TB_SSM), nullptr);
.LBB0_1792:
	s_andn2_b64 vcc, exec, s[2:3]
	s_cbranch_vccnz .LBB0_1888
	s_mov_b64 s[2:3], 0
	v_readlane_b32 s4, v241, 1
	v_readlane_b32 s5, v241, 2
	s_add_u32 s6, s4, s2
	s_addc_u32 s7, s5, s3
	v_readlane_b32 s4, v240, 40
	v_readlane_b32 s5, v240, 41
	v_mov_b32_e32 v3, v182
	s_andn2_b64 vcc, exec, s[4:5]
	v_cndmask_b32_e64 v0, 0, 1, s[4:5]
	v_cmp_ne_u32_e64 s[2:3], 1, v0
	s_cbranch_vccnz .LBB0_1818
	v_and_b32_e32 v14, 1, v3
	v_lshlrev_b32_e32 v144, 5, v14
	s_waitcnt lgkmcnt(0)
	v_lshl_add_u64 v[0:1], s[6:7], 0, v[144:145]
	s_mov_b64 s[4:5], 0x61a4100
	v_ashrrev_i32_e32 v2, 1, v3
	v_lshl_add_u64 v[0:1], v[0:1], 0, s[4:5]
	v_readlane_b32 s4, v240, 42
	v_lshlrev_b32_e32 v3, 2, v3
	s_nop 0
	v_add_u32_e32 v4, s4, v2
	v_ashrrev_i32_e32 v5, 31, v4
	v_lshlrev_b64 v[4:5], 6, v[4:5]
	v_lshl_add_u64 v[4:5], v[0:1], 0, v[4:5]
	global_load_dwordx4 v[6:9], v[4:5], off
	global_load_dwordx4 v[10:13], v[4:5], off offset:16
	v_readlane_b32 s10, v238, 63
	v_readlane_b32 s11, v237, 0
	s_nop 3
	s_andn2_b64 vcc, exec, s[10:11]
	s_cbranch_vccnz .Lpf_w1_done
	v_readlane_b32 s9, v239, 31
	s_nop 3
	v_add_u32_e32 v72, s9, v2
	v_ashrrev_i32_e32 v73, 31, v72
	v_lshlrev_b64 v[72:73], 6, v[72:73]
	v_lshl_add_u64 v[72:73], v[0:1], 0, v[72:73]
	global_load_dwordx4 v[16:19], v[72:73], off
	global_load_dwordx4 v[20:23], v[72:73], off offset:16
	v_readlane_b32 s10, v239, 55
	v_readlane_b32 s11, v239, 56
	s_nop 3
	s_andn2_b64 vcc, exec, s[10:11]
	s_cbranch_vccnz .Lpf_w1_done
	v_readlane_b32 s9, v239, 32
	s_nop 3
	v_add_u32_e32 v72, s9, v2
	v_ashrrev_i32_e32 v73, 31, v72
	v_lshlrev_b64 v[72:73], 6, v[72:73]
	v_lshl_add_u64 v[72:73], v[0:1], 0, v[72:73]
	global_load_dwordx4 v[24:27], v[72:73], off
	global_load_dwordx4 v[28:31], v[72:73], off offset:16
	v_readlane_b32 s10, v238, 1
	v_readlane_b32 s11, v238, 2
	s_nop 3
	s_andn2_b64 vcc, exec, s[10:11]
	s_cbranch_vccnz .Lpf_w1_done
	v_readlane_b32 s9, v239, 33
	s_nop 3
	v_add_u32_e32 v72, s9, v2
	v_ashrrev_i32_e32 v73, 31, v72
	v_lshlrev_b64 v[72:73], 6, v[72:73]
	v_lshl_add_u64 v[72:73], v[0:1], 0, v[72:73]
	global_load_dwordx4 v[32:35], v[72:73], off
	global_load_dwordx4 v[36:39], v[72:73], off offset:16
	v_readlane_b32 s10, v238, 7
	v_readlane_b32 s11, v238, 8
	s_nop 3
	s_andn2_b64 vcc, exec, s[10:11]
	s_cbranch_vccnz .Lpf_w1_done
	v_readlane_b32 s9, v239, 34
	s_nop 3
	v_add_u32_e32 v72, s9, v2
	v_ashrrev_i32_e32 v73, 31, v72
	v_lshlrev_b64 v[72:73], 6, v[72:73]
	v_lshl_add_u64 v[72:73], v[0:1], 0, v[72:73]
	global_load_dwordx4 v[40:43], v[72:73], off
	global_load_dwordx4 v[44:47], v[72:73], off offset:16
	v_readlane_b32 s10, v238, 13
	v_readlane_b32 s11, v238, 14
	s_nop 3
	s_andn2_b64 vcc, exec, s[10:11]
	s_cbranch_vccnz .Lpf_w1_done
	v_readlane_b32 s9, v239, 35
	s_nop 3
	v_add_u32_e32 v72, s9, v2
	v_ashrrev_i32_e32 v73, 31, v72
	v_lshlrev_b64 v[72:73], 6, v[72:73]
	v_lshl_add_u64 v[72:73], v[0:1], 0, v[72:73]
	global_load_dwordx4 v[48:51], v[72:73], off
	global_load_dwordx4 v[52:55], v[72:73], off offset:16
	v_readlane_b32 s10, v238, 19
	v_readlane_b32 s11, v238, 20
	s_nop 3
	s_andn2_b64 vcc, exec, s[10:11]
	s_cbranch_vccnz .Lpf_w1_done
	v_readlane_b32 s9, v239, 36
	s_nop 3
	v_add_u32_e32 v72, s9, v2
	v_ashrrev_i32_e32 v73, 31, v72
	v_lshlrev_b64 v[72:73], 6, v[72:73]
	v_lshl_add_u64 v[72:73], v[0:1], 0, v[72:73]
	global_load_dwordx4 v[56:59], v[72:73], off
	global_load_dwordx4 v[60:63], v[72:73], off offset:16
	v_readlane_b32 s10, v238, 25
	v_readlane_b32 s11, v238, 26
	s_nop 3
	s_andn2_b64 vcc, exec, s[10:11]
	s_cbranch_vccnz .Lpf_w1_done
	v_readlane_b32 s9, v239, 37
	s_nop 3
	v_add_u32_e32 v72, s9, v2
	v_ashrrev_i32_e32 v73, 31, v72
	v_lshlrev_b64 v[72:73], 6, v[72:73]
	v_lshl_add_u64 v[72:73], v[0:1], 0, v[72:73]
	global_load_dwordx4 v[64:67], v[72:73], off
	global_load_dwordx4 v[68:71], v[72:73], off offset:16

; DI void norm_prepass(const float* __restrict__ ss, const pg8::StaticOrder& S, LAS float* tab) {
;     ...
;   for (int i = 0; i < 8 && S.next(i, u); ++i) {
;     const f32x4* sp = (const f32x4*)(ss + (size_t)(u.pm * 256 + row) * 16 + half * 8);
;     const f32x4 a = sp[0], b = sp[1];
;     float t = a[0]; t += a[1]; t += a[2]; t += a[3]; t += b[0]; t += b[1]; t += b[2]; t += b[3];
;     const float o = shx(t, 1, tid & 63);
;     const float tot = half ? (o + t) : (t + o);
;     if (!half) tab[i * 256 + row] = rsqrtf(tot * (1.f / 1024.f) + EPS);
.LBB0_1796:
	s_or_b64 exec, exec, s[10:11]
	v_readlane_b32 s10, v238, 63
	v_readlane_b32 s11, v237, 0
	s_andn2_b64 vcc, exec, s[10:11]
	s_cbranch_vccnz .LBB0_1818
	v_readlane_b32 s9, v239, 31
	s_waitcnt lgkmcnt(0)
	s_nop 0
	v_add_f32_e32 v5, v16, v17
	v_add_f32_e32 v5, v18, v5
	v_add_f32_e32 v5, v19, v5
	v_add_f32_e32 v5, v20, v5
	v_add_f32_e32 v5, v21, v5
	v_add_f32_e32 v5, v22, v5
	v_add_f32_e32 v5, v23, v5
	ds_bpermute_b32 v6, v4, v5
	s_and_saveexec_b64 s[10:11], s[4:5]
	s_cbranch_execz .LBB0_1799
	s_waitcnt lgkmcnt(0)
	v_add_f32_e32 v5, v5, v6
	v_fmamk_f32 v5, v5, 0x3a800000, v184
	s_mov_b32 s9, 0x800000
	v_mul_f32_e32 v6, 0x4b800000, v5
	v_cmp_gt_f32_e32 vcc, s9, v5
	s_nop 1
	v_cndmask_b32_e32 v5, v5, v6, vcc
	v_rsq_f32_e32 v5, v5
	s_nop 0
	v_mul_f32_e32 v6, 0x45800000, v5
	v_cndmask_b32_e32 v5, v5, v6, vcc
	ds_write_b32 v3, v5 offset:1024
.LBB0_1799:
	s_or_b64 exec, exec, s[10:11]
	v_readlane_b32 s10, v239, 55
	v_readlane_b32 s11, v239, 56
	s_andn2_b64 vcc, exec, s[10:11]
	s_cbranch_vccnz .LBB0_1818
	v_readlane_b32 s9, v239, 32
	s_waitcnt lgkmcnt(0)
	s_nop 0
	v_add_f32_e32 v5, v24, v25
	v_add_f32_e32 v5, v26, v5
	v_add_f32_e32 v5, v27, v5
	v_add_f32_e32 v5, v28, v5
	v_add_f32_e32 v5, v29, v5
	v_add_f32_e32 v5, v30, v5
	v_add_f32_e32 v5, v31, v5
	ds_bpermute_b32 v6, v4, v5
	s_and_saveexec_b64 s[10:11], s[4:5]
	s_cbranch_execz .LBB0_1802
	s_waitcnt lgkmcnt(0)
	v_add_f32_e32 v5, v5, v6
	v_fmamk_f32 v5, v5, 0x3a800000, v184
	s_mov_b32 s9, 0x800000
	v_mul_f32_e32 v6, 0x4b800000, v5
	v_cmp_gt_f32_e32 vcc, s9, v5
	s_nop 1
	v_cndmask_b32_e32 v5, v5, v6, vcc
	v_rsq_f32_e32 v5, v5
	s_nop 0
	v_mul_f32_e32 v6, 0x45800000, v5
	v_cndmask_b32_e32 v5, v5, v6, vcc
	ds_write_b32 v3, v5 offset:2048
.LBB0_1802:
	s_or_b64 exec, exec, s[10:11]
	v_readlane_b32 s10, v238, 1
	v_readlane_b32 s11, v238, 2
	s_andn2_b64 vcc, exec, s[10:11]
	s_cbranch_vccnz .LBB0_1818
	v_readlane_b32 s9, v239, 33
	s_waitcnt lgkmcnt(0)
	s_nop 0
	v_add_f32_e32 v5, v32, v33
	v_add_f32_e32 v5, v34, v5
	v_add_f32_e32 v5, v35, v5
	v_add_f32_e32 v5, v36, v5
	v_add_f32_e32 v5, v37, v5
	v_add_f32_e32 v5, v38, v5
	v_add_f32_e32 v5, v39, v5
	ds_bpermute_b32 v6, v4, v5
	s_and_saveexec_b64 s[10:11], s[4:5]
	s_cbranch_execz .LBB0_1805
	s_waitcnt lgkmcnt(0)
	v_add_f32_e32 v5, v5, v6
	v_fmamk_f32 v5, v5, 0x3a800000, v184
	s_mov_b32 s9, 0x800000
	v_mul_f32_e32 v6, 0x4b800000, v5
	v_cmp_gt_f32_e32 vcc, s9, v5
	s_nop 1
	v_cndmask_b32_e32 v5, v5, v6, vcc
	v_rsq_f32_e32 v5, v5
	s_nop 0
	v_mul_f32_e32 v6, 0x45800000, v5
	v_cndmask_b32_e32 v5, v5, v6, vcc
	ds_write_b32 v3, v5 offset:3072
.LBB0_1805:
	s_or_b64 exec, exec, s[10:11]
	v_readlane_b32 s10, v238, 7
	v_readlane_b32 s11, v238, 8
	s_andn2_b64 vcc, exec, s[10:11]
	s_cbranch_vccnz .LBB0_1818
	v_readlane_b32 s9, v239, 34
	s_waitcnt lgkmcnt(0)
	s_nop 0
	v_add_f32_e32 v5, v40, v41
	v_add_f32_e32 v5, v42, v5
	v_add_f32_e32 v5, v43, v5
	v_add_f32_e32 v5, v44, v5
	v_add_f32_e32 v5, v45, v5
	v_add_f32_e32 v5, v46, v5
	v_add_f32_e32 v5, v47, v5
	ds_bpermute_b32 v6, v4, v5
	s_and_saveexec_b64 s[10:11], s[4:5]
	s_cbranch_execz .LBB0_1808
	s_waitcnt lgkmcnt(0)
	v_add_f32_e32 v5, v5, v6
	v_fmamk_f32 v5, v5, 0x3a800000, v184
	s_mov_b32 s9, 0x800000
	v_mul_f32_e32 v6, 0x4b800000, v5
	v_cmp_gt_f32_e32 vcc, s9, v5
	s_nop 1
	v_cndmask_b32_e32 v5, v5, v6, vcc
	v_rsq_f32_e32 v5, v5
	s_nop 0
	v_mul_f32_e32 v6, 0x45800000, v5
	v_cndmask_b32_e32 v5, v5, v6, vcc
	ds_write_b32 v3, v5 offset:4096
.LBB0_1808:
	s_or_b64 exec, exec, s[10:11]
	v_readlane_b32 s10, v238, 13
	v_readlane_b32 s11, v238, 14
	s_andn2_b64 vcc, exec, s[10:11]
	s_cbranch_vccnz .LBB0_1818
	v_readlane_b32 s9, v239, 35
	s_waitcnt lgkmcnt(0)
	s_nop 0
	v_add_f32_e32 v5, v48, v49
	v_add_f32_e32 v5, v50, v5
	v_add_f32_e32 v5, v51, v5
	v_add_f32_e32 v5, v52, v5
	v_add_f32_e32 v5, v53, v5
	v_add_f32_e32 v5, v54, v5
	v_add_f32_e32 v5, v55, v5
	ds_bpermute_b32 v6, v4, v5
	s_and_saveexec_b64 s[10:11], s[4:5]
	s_cbranch_execz .LBB0_1811
	s_waitcnt lgkmcnt(0)
	v_add_f32_e32 v5, v5, v6
	v_fmamk_f32 v5, v5, 0x3a800000, v184
	s_mov_b32 s9, 0x800000
	v_mul_f32_e32 v6, 0x4b800000, v5
	v_cmp_gt_f32_e32 vcc, s9, v5
	s_nop 1
	v_cndmask_b32_e32 v5, v5, v6, vcc
	v_rsq_f32_e32 v5, v5
	s_nop 0
	v_mul_f32_e32 v6, 0x45800000, v5
	v_cndmask_b32_e32 v5, v5, v6, vcc
	ds_write_b32 v3, v5 offset:5120
.LBB0_1811:
	s_or_b64 exec, exec, s[10:11]
	v_readlane_b32 s10, v238, 19
	v_readlane_b32 s11, v238, 20
	s_andn2_b64 vcc, exec, s[10:11]
	s_cbranch_vccnz .LBB0_1818
	v_readlane_b32 s9, v239, 36
	s_waitcnt lgkmcnt(0)
	s_nop 0
	v_add_f32_e32 v5, v56, v57
	v_add_f32_e32 v5, v58, v5
	v_add_f32_e32 v5, v59, v5
	v_add_f32_e32 v5, v60, v5
	v_add_f32_e32 v5, v61, v5
	v_add_f32_e32 v5, v62, v5
	v_add_f32_e32 v5, v63, v5
	ds_bpermute_b32 v6, v4, v5
	s_and_saveexec_b64 s[10:11], s[4:5]
	s_cbranch_execz .LBB0_1814
	s_waitcnt lgkmcnt(0)
	v_add_f32_e32 v5, v5, v6
	v_fmamk_f32 v5, v5, 0x3a800000, v184
	s_mov_b32 s9, 0x800000
	v_mul_f32_e32 v6, 0x4b800000, v5
	v_cmp_gt_f32_e32 vcc, s9, v5
	s_nop 1
	v_cndmask_b32_e32 v5, v5, v6, vcc
	v_rsq_f32_e32 v5, v5
	s_nop 0
	v_mul_f32_e32 v6, 0x45800000, v5
	v_cndmask_b32_e32 v5, v5, v6, vcc
	ds_write_b32 v3, v5 offset:6144
.LBB0_1814:
	s_or_b64 exec, exec, s[10:11]
	v_readlane_b32 s10, v238, 25
	v_readlane_b32 s11, v238, 26
	s_andn2_b64 vcc, exec, s[10:11]
	s_cbranch_vccnz .LBB0_1818
	v_readlane_b32 s9, v239, 37
	s_waitcnt lgkmcnt(0)
	s_nop 0
	v_add_f32_e32 v0, v64, v65
	v_add_f32_e32 v0, v66, v0
	v_add_f32_e32 v0, v67, v0
	v_add_f32_e32 v0, v68, v0
	v_add_f32_e32 v0, v69, v0
	v_add_f32_e32 v0, v70, v0
	v_add_f32_e32 v0, v71, v0
	ds_bpermute_b32 v1, v4, v0
	s_and_saveexec_b64 s[10:11], s[4:5]
	s_cbranch_execz .LBB0_1817
	s_waitcnt lgkmcnt(0)
	v_add_f32_e32 v0, v0, v1
	v_fmamk_f32 v0, v0, 0x3a800000, v184
	s_mov_b32 s4, 0x800000
	v_mul_f32_e32 v1, 0x4b800000, v0
	v_cmp_gt_f32_e32 vcc, s4, v0
	s_nop 1
	v_cndmask_b32_e32 v0, v0, v1, vcc
	v_rsq_f32_e32 v0, v0
	s_nop 0
	v_mul_f32_e32 v1, 0x45800000, v0
	v_cndmask_b32_e32 v0, v0, v1, vcc
	ds_write_b32 v3, v0 offset:7168
